# v21 + group barriers arrive with a non-returning atomic and a static release target (k * group size)
# speedup vs baseline: 1.0026x; 1.0026x over previous
; __device__ __forceinline__ unsigned xb_ld(unsigned* p)              { return __hip_atomic_load(p, __ATOMIC_RELAXED, __HIP_MEMORY_SCOPE_AGENT); }
; __device__ __forceinline__ unsigned xb_add(unsigned* p, unsigned v) { return __hip_atomic_fetch_add(p, v, __ATOMIC_RELAXED, __HIP_MEMORY_SCOPE_AGENT); }
; __device__ __forceinline__ void group_barrier(unsigned* cnt, unsigned gs, bool light) {
;     asm volatile("s_waitcnt vmcnt(0)" ::: "memory");
;     __syncthreads();
;     if (threadIdx.x == 0) {
;         if (!light) { __builtin_amdgcn_fence(__ATOMIC_RELEASE, "agent"); asm volatile("s_waitcnt vmcnt(0)" ::: "memory"); }
;         const unsigned old = xb_add(cnt, 1u);
;         const unsigned target = (old / gs + 1u) * gs;
;         unsigned sp = 0u;
;         while (xb_ld(cnt) < target) { __builtin_amdgcn_s_sleep(1); if (++sp > (1u << 22)) break; }
; __global__ void __launch_bounds__(NWAVES * 64, 2) hymba_fwd(Args args) {
;     ...
;     group_barrier(gcnt, gsz, light);
.LBB0_451:
	s_mov_b64 s[8:9], exec
	v_mbcnt_lo_u32_b32 v0, s8, 0
	v_mbcnt_hi_u32_b32 v0, s9, v0
	v_cmp_eq_u32_e32 vcc, 0, v0
	s_and_saveexec_b64 s[6:7], vcc
	s_cbranch_execz .LBB0_453
	s_bcnt1_i32_b64 s3, s[8:9]
	v_mov_b32_e32 v1, 0
	v_mov_b32_e32 v2, s3
	global_atomic_add v1, v2, s[64:65]
.LBB0_453:
	s_or_b64 exec, exec, s[6:7]
	s_mul_i32 s6, s33, 1
	v_mov_b32_e32 v0, s6
	s_mov_b32 s3, 0x400001
	s_mov_b64 s[6:7], 0
	v_mov_b32_e32 v1, 0
	s_branch .LBB0_459

; __device__ __forceinline__ unsigned xb_ld(unsigned* p)              { return __hip_atomic_load(p, __ATOMIC_RELAXED, __HIP_MEMORY_SCOPE_AGENT); }
; __device__ __forceinline__ unsigned xb_add(unsigned* p, unsigned v) { return __hip_atomic_fetch_add(p, v, __ATOMIC_RELAXED, __HIP_MEMORY_SCOPE_AGENT); }
; __device__ __forceinline__ void group_barrier(unsigned* cnt, unsigned gs, bool light) {
;     asm volatile("s_waitcnt vmcnt(0)" ::: "memory");
;     __syncthreads();
;     if (threadIdx.x == 0) {
;         if (!light) { __builtin_amdgcn_fence(__ATOMIC_RELEASE, "agent"); asm volatile("s_waitcnt vmcnt(0)" ::: "memory"); }
;         const unsigned old = xb_add(cnt, 1u);
;         const unsigned target = (old / gs + 1u) * gs;
;         unsigned sp = 0u;
;         while (xb_ld(cnt) < target) { __builtin_amdgcn_s_sleep(1); if (++sp > (1u << 22)) break; }
; __global__ void __launch_bounds__(NWAVES * 64, 2) hymba_fwd(Args args) {
;     ...
;     group_barrier(gcnt, gsz, light);
.LBB0_509:
	s_mov_b64 s[16:17], exec
	v_mbcnt_lo_u32_b32 v0, s16, 0
	v_mbcnt_hi_u32_b32 v0, s17, v0
	v_cmp_eq_u32_e32 vcc, 0, v0
	s_and_saveexec_b64 s[14:15], vcc
	s_cbranch_execz .LBB0_511
	s_bcnt1_i32_b64 s2, s[16:17]
	v_mov_b32_e32 v1, 0
	v_mov_b32_e32 v2, s2
	global_atomic_add v1, v2, s[64:65]
.LBB0_511:
	s_or_b64 exec, exec, s[14:15]
	s_mul_i32 s2, s33, 2
	v_mov_b32_e32 v0, s2
	s_mov_b32 s3, 0x400001
	s_mov_b64 s[14:15], 0
	v_mov_b32_e32 v1, 0
	s_branch .LBB0_517

; __device__ __forceinline__ unsigned xb_ld(unsigned* p)              { return __hip_atomic_load(p, __ATOMIC_RELAXED, __HIP_MEMORY_SCOPE_AGENT); }
; __device__ __forceinline__ unsigned xb_add(unsigned* p, unsigned v) { return __hip_atomic_fetch_add(p, v, __ATOMIC_RELAXED, __HIP_MEMORY_SCOPE_AGENT); }
; __device__ __forceinline__ void group_barrier(unsigned* cnt, unsigned gs, bool light) {
;     asm volatile("s_waitcnt vmcnt(0)" ::: "memory");
;     __syncthreads();
;     if (threadIdx.x == 0) {
;         if (!light) { __builtin_amdgcn_fence(__ATOMIC_RELEASE, "agent"); asm volatile("s_waitcnt vmcnt(0)" ::: "memory"); }
;         const unsigned old = xb_add(cnt, 1u);
;         const unsigned target = (old / gs + 1u) * gs;
;         unsigned sp = 0u;
;         while (xb_ld(cnt) < target) { __builtin_amdgcn_s_sleep(1); if (++sp > (1u << 22)) break; }
; __global__ void __launch_bounds__(NWAVES * 64, 2) hymba_fwd(Args args) {
;     ...
;     group_barrier(gcnt, gsz, light);
.LBB0_544:
	s_mov_b64 s[14:15], exec
	v_mbcnt_lo_u32_b32 v0, s14, 0
	v_mbcnt_hi_u32_b32 v0, s15, v0
	v_cmp_eq_u32_e32 vcc, 0, v0
	s_and_saveexec_b64 s[8:9], vcc
	s_cbranch_execz .LBB0_546
	s_bcnt1_i32_b64 s2, s[14:15]
	v_mov_b32_e32 v1, 0
	v_mov_b32_e32 v2, s2
	global_atomic_add v1, v2, s[64:65]
.LBB0_546:
	s_or_b64 exec, exec, s[8:9]
	s_mul_i32 s2, s33, 3
	v_mov_b32_e32 v0, s2
	s_mov_b32 s3, 0x400001
	s_mov_b64 s[8:9], 0
	v_mov_b32_e32 v1, 0
	s_branch .LBB0_552
